# combo6 without the phase-repeat timing hook at the phase-loop head (final candidate)
# baseline (speedup 1.0000x reference)
.LBB0_9:
	s_bitcmp1_b32 s23, 0
	s_cselect_b64 s[0:1], -1, 0
	s_and_b64 vcc, exec, s[0:1]
	s_cbranch_vccnz .LBB0_7
	s_ashr_i32 s6, s23, 1
	s_mul_hi_i32 s0, s6, 0x66666667
	s_lshr_b32 s1, s0, 31
	s_ashr_i32 s0, s0, 3
	s_add_i32 s8, s0, s1
	s_mov_b32 s0, s8
	v_mbcnt_lo_u32_b32 v179, -1, 0
	v_mbcnt_hi_u32_b32 v179, -1, v179
	v_writelane_b32 v248, s0, 0
	s_mov_b32 s22, 2
	s_nop 0
	v_writelane_b32 v248, s1, 1
	s_mul_i32 s0, s8, 20
	s_sub_i32 s1, s6, s0
	s_cmp_lt_i32 s1, 7
	s_cselect_b32 s0, 13, -3
	s_cmp_gt_i32 s1, 3
	s_cselect_b32 s70, s0, 0
	s_add_i32 s70, s70, s1
	v_readlane_b32 s0, v251, 6
	v_readlane_b32 s8, v249, 25
	v_writelane_b32 v248, s6, 2
	v_add_u32_e32 v178, s0, v179
	v_readlane_b32 s10, v249, 27
	v_readlane_b32 s11, v249, 28
	s_cmp_lg_u32 s70, 1
	v_writelane_b32 v248, s1, 3
	s_mov_b64 s[90:91], s[10:11]
	v_readfirstlane_b32 s14, v178
	s_cselect_b64 s[0:1], -1, 0
	s_cmp_eq_u32 s70, 1
	v_readlane_b32 s9, v249, 26
	s_cbranch_scc1 .LBB0_30
	s_cmp_lt_i32 s70, 10
	s_cbranch_scc1 .LBB0_15
	s_cmp_gt_i32 s70, 11
	s_cbranch_scc0 .LBB0_16
	s_cmp_gt_i32 s70, 13
	s_cbranch_scc0 .LBB0_17
	s_cmp_lg_u32 s70, 14
	s_mov_b64 s[8:9], -1
	s_cselect_b64 s[10:11], -1, 0
	s_cbranch_execz .LBB0_18
	s_branch .LBB0_19
